# SwiGLU epilogues of both FFN-up GEMMs rewritten: packed f32 mul/add, batched exp/rcp, rstd via v_rsq_f32 computed once per row group (no serial IEEE sqrt/div chains)
# speedup vs baseline: 1.0178x; 1.0114x over previous
; __device__ __forceinline__ u32x4 pack8(f32x4 a, f32x4 b) { u32x4 o; o.x = cvt_pk(a.x, a.y); o.y = cvt_pk(a.z, a.w); o.z = cvt_pk(b.x, b.y); o.w = cvt_pk(b.z, b.w); return o; }
; __device__ __forceinline__ float rstd_of(const float* SS, int row, float invw) { return 1.0f / sqrtf(SS[row] * invw + EPS); }
; __device__ __forceinline__ float silu_f(float g) { return g * __builtin_amdgcn_rcpf(1.f + __builtin_amdgcn_exp2f(-1.4426950408889634f * g)); }
;     __device__ __forceinline__ void operator()(const f32x4 (&acc)[2][2][4][2], const pg8::Unit& u, int wr, int wc, int fr, int fq) const {
;     ...
;         bf16_t* hb = H + (size_t)u.pm * 256 * FF + (size_t)(col0 >> 6) * (256 * 64) + (col0 & 63);
; #pragma unroll
;         for (int ai = 0; ai < 2; ++ai)
; #pragma unroll
;             for (int m = 0; m < 4; ++m) {
;                 const int row = row0 + ai * 128 + m * 16;
;                 const float r = SCALE ? rstd_of(SS, row, 1.f / 1024.f) : 1.f;
;                 const f32x4 g0 = acc[ai][0][m][0] * r, g1 = acc[ai][0][m][1] * r, u0 = acc[ai][1][m][0] * r, u1 = acc[ai][1][m][1] * r;
;                 f32x4 h0, h1;
;                 h0.x = silu_f(g0.x) * u0.x; h0.y = silu_f(g0.y) * u0.y; h0.z = silu_f(g0.z) * u0.z; h0.w = silu_f(g0.w) * u0.w;
;                 h1.x = silu_f(g1.x) * u1.x; h1.y = silu_f(g1.y) * u1.y; h1.z = silu_f(g1.z) * u1.z; h1.w = silu_f(g1.w) * u1.w;
;                 *(u32x4*)(hb + (wr * 64 + fr + ai * 128 + m * 16) * 64) = pack8(h0, h1);
;             }
.LBB0_178:
	s_lshl_b32 s15, s46, 7
	s_or_b32 s15, s15, s40
	s_mul_hi_i32 s17, s22, 0x160000
	s_mul_i32 s22, s22, 0x160000
	s_add_u32 s22, s64, s22
	s_addc_u32 s17, s65, s17
	s_ashr_i32 s24, s15, 6
	s_ashr_i32 s25, s24, 31
	s_lshl_b64 s[24:25], s[24:25], 15
	s_add_u32 s24, s22, s24
	s_addc_u32 s25, s17, s25
	v_mov_b32_e32 v162, 0xbfb8aa3b
	v_mov_b32_e32 v163, 0xbfb8aa3b
	v_mov_b32_e32 v164, 1.0
	v_mov_b32_e32 v165, 1.0
	v_lshl_add_u64 v[156:157], s[24:25], 0, v[136:137]
	v_lshl_add_u64 v[168:169], v[138:139], 1, v[156:157]
	v_add_co_u32_e32 v170, vcc, s45, v168
	v_addc_co_u32_e32 v171, vcc, 0, v169, vcc
	v_lshl_add_u64 v[172:173], v[140:141], 1, v[156:157]
	v_lshl_add_u64 v[174:175], v[142:143], 1, v[156:157]
	v_lshl_add_u64 v[176:177], v[144:145], 1, v[156:157]
	v_lshl_add_u64 v[194:195], v[146:147], 1, v[156:157]
	v_pk_mul_f32 v[178:179], v[124:125], v[162:163]
	v_pk_mul_f32 v[180:181], v[126:127], v[162:163]
	v_pk_mul_f32 v[182:183], v[120:121], v[162:163]
	v_pk_mul_f32 v[184:185], v[122:123], v[162:163]
	v_exp_f32_e32 v178, v178
	v_exp_f32_e32 v179, v179
	v_exp_f32_e32 v180, v180
	v_exp_f32_e32 v181, v181
	v_exp_f32_e32 v182, v182
	v_exp_f32_e32 v183, v183
	v_exp_f32_e32 v184, v184
	v_exp_f32_e32 v185, v185
	v_pk_add_f32 v[178:179], v[178:179], v[164:165]
	v_pk_add_f32 v[180:181], v[180:181], v[164:165]
	v_pk_add_f32 v[182:183], v[182:183], v[164:165]
	v_pk_add_f32 v[184:185], v[184:185], v[164:165]
	v_rcp_f32_e32 v178, v178
	v_rcp_f32_e32 v179, v179
	v_rcp_f32_e32 v180, v180
	v_rcp_f32_e32 v181, v181
	v_rcp_f32_e32 v182, v182
	v_rcp_f32_e32 v183, v183
	v_rcp_f32_e32 v184, v184
	v_rcp_f32_e32 v185, v185
	v_pk_mul_f32 v[178:179], v[124:125], v[178:179]
	v_pk_mul_f32 v[180:181], v[126:127], v[180:181]
	v_pk_mul_f32 v[182:183], v[120:121], v[182:183]
	v_pk_mul_f32 v[184:185], v[122:123], v[184:185]
	v_pk_mul_f32 v[178:179], v[178:179], v[116:117]
	v_pk_mul_f32 v[180:181], v[180:181], v[118:119]
	v_pk_mul_f32 v[182:183], v[182:183], v[112:113]
	v_pk_mul_f32 v[184:185], v[184:185], v[114:115]
	v_cvt_pk_bf16_f32 v112, v178, v179
	v_cvt_pk_bf16_f32 v113, v180, v181
	v_cvt_pk_bf16_f32 v114, v182, v183
	v_cvt_pk_bf16_f32 v115, v184, v185
	global_store_dwordx4 v[168:169], v[112:115], off
	v_pk_mul_f32 v[186:187], v[108:109], v[162:163]
	v_pk_mul_f32 v[188:189], v[110:111], v[162:163]
	v_pk_mul_f32 v[190:191], v[104:105], v[162:163]
	v_pk_mul_f32 v[192:193], v[106:107], v[162:163]
	v_exp_f32_e32 v186, v186
	v_exp_f32_e32 v187, v187
	v_exp_f32_e32 v188, v188
	v_exp_f32_e32 v189, v189
	v_exp_f32_e32 v190, v190
	v_exp_f32_e32 v191, v191
	v_exp_f32_e32 v192, v192
	v_exp_f32_e32 v193, v193
	v_pk_add_f32 v[186:187], v[186:187], v[164:165]
	v_pk_add_f32 v[188:189], v[188:189], v[164:165]
	v_pk_add_f32 v[190:191], v[190:191], v[164:165]
	v_pk_add_f32 v[192:193], v[192:193], v[164:165]
	v_rcp_f32_e32 v186, v186
	v_rcp_f32_e32 v187, v187
	v_rcp_f32_e32 v188, v188
	v_rcp_f32_e32 v189, v189
	v_rcp_f32_e32 v190, v190
	v_rcp_f32_e32 v191, v191
	v_rcp_f32_e32 v192, v192
	v_rcp_f32_e32 v193, v193
	v_pk_mul_f32 v[186:187], v[108:109], v[186:187]
	v_pk_mul_f32 v[188:189], v[110:111], v[188:189]
	v_pk_mul_f32 v[190:191], v[104:105], v[190:191]
	v_pk_mul_f32 v[192:193], v[106:107], v[192:193]
	v_pk_mul_f32 v[186:187], v[186:187], v[100:101]
	v_pk_mul_f32 v[188:189], v[188:189], v[102:103]
	v_pk_mul_f32 v[190:191], v[190:191], v[96:97]
	v_pk_mul_f32 v[192:193], v[192:193], v[98:99]
	v_cvt_pk_bf16_f32 v96, v186, v187
	v_cvt_pk_bf16_f32 v97, v188, v189
	v_cvt_pk_bf16_f32 v98, v190, v191
	v_cvt_pk_bf16_f32 v99, v192, v193
	global_store_dwordx4 v[168:169], v[96:99], off offset:2048
	v_pk_mul_f32 v[178:179], v[92:93], v[162:163]
	v_pk_mul_f32 v[180:181], v[94:95], v[162:163]
	v_pk_mul_f32 v[182:183], v[88:89], v[162:163]
	v_pk_mul_f32 v[184:185], v[90:91], v[162:163]
	v_exp_f32_e32 v178, v178
	v_exp_f32_e32 v179, v179
	v_exp_f32_e32 v180, v180
	v_exp_f32_e32 v181, v181
	v_exp_f32_e32 v182, v182
	v_exp_f32_e32 v183, v183
	v_exp_f32_e32 v184, v184
	v_exp_f32_e32 v185, v185
	v_pk_add_f32 v[178:179], v[178:179], v[164:165]
	v_pk_add_f32 v[180:181], v[180:181], v[164:165]
	v_pk_add_f32 v[182:183], v[182:183], v[164:165]
	v_pk_add_f32 v[184:185], v[184:185], v[164:165]
	v_rcp_f32_e32 v178, v178
	v_rcp_f32_e32 v179, v179
	v_rcp_f32_e32 v180, v180
	v_rcp_f32_e32 v181, v181
	v_rcp_f32_e32 v182, v182
	v_rcp_f32_e32 v183, v183
	v_rcp_f32_e32 v184, v184
	v_rcp_f32_e32 v185, v185
	v_pk_mul_f32 v[178:179], v[92:93], v[178:179]
	v_pk_mul_f32 v[180:181], v[94:95], v[180:181]
	v_pk_mul_f32 v[182:183], v[88:89], v[182:183]
	v_pk_mul_f32 v[184:185], v[90:91], v[184:185]
	v_pk_mul_f32 v[178:179], v[178:179], v[84:85]
	v_pk_mul_f32 v[180:181], v[180:181], v[86:87]
	v_pk_mul_f32 v[182:183], v[182:183], v[80:81]
	v_pk_mul_f32 v[184:185], v[184:185], v[82:83]
	v_cvt_pk_bf16_f32 v80, v178, v179
	v_cvt_pk_bf16_f32 v81, v180, v181
	v_cvt_pk_bf16_f32 v82, v182, v183
	v_cvt_pk_bf16_f32 v83, v184, v185
	global_store_dwordx4 v[170:171], v[80:83], off
	v_pk_mul_f32 v[186:187], v[76:77], v[162:163]
	v_pk_mul_f32 v[188:189], v[78:79], v[162:163]
	v_pk_mul_f32 v[190:191], v[72:73], v[162:163]
	v_pk_mul_f32 v[192:193], v[74:75], v[162:163]
	v_exp_f32_e32 v186, v186
	v_exp_f32_e32 v187, v187
	v_exp_f32_e32 v188, v188
	v_exp_f32_e32 v189, v189
	v_exp_f32_e32 v190, v190
	v_exp_f32_e32 v191, v191
	v_exp_f32_e32 v192, v192
	v_exp_f32_e32 v193, v193
	v_pk_add_f32 v[186:187], v[186:187], v[164:165]
	v_pk_add_f32 v[188:189], v[188:189], v[164:165]
	v_pk_add_f32 v[190:191], v[190:191], v[164:165]
	v_pk_add_f32 v[192:193], v[192:193], v[164:165]
	v_rcp_f32_e32 v186, v186
	v_rcp_f32_e32 v187, v187
	v_rcp_f32_e32 v188, v188
; __device__ __forceinline__ u32x4 pack8(f32x4 a, f32x4 b) { u32x4 o; o.x = cvt_pk(a.x, a.y); o.y = cvt_pk(a.z, a.w); o.z = cvt_pk(b.x, b.y); o.w = cvt_pk(b.z, b.w); return o; }
; __device__ __forceinline__ float rstd_of(const float* SS, int row, float invw) { return 1.0f / sqrtf(SS[row] * invw + EPS); }
; __device__ __forceinline__ float silu_f(float g) { return g * __builtin_amdgcn_rcpf(1.f + __builtin_amdgcn_exp2f(-1.4426950408889634f * g)); }
;     __device__ __forceinline__ void operator()(const f32x4 (&acc)[2][2][4][2], const pg8::Unit& u, int wr, int wc, int fr, int fq) const {
;     ...
;         for (int ai = 0; ai < 2; ++ai)
; #pragma unroll
;             for (int m = 0; m < 4; ++m) {
;                 const int row = row0 + ai * 128 + m * 16;
;                 const float r = SCALE ? rstd_of(SS, row, 1.f / 1024.f) : 1.f;
;                 const f32x4 g0 = acc[ai][0][m][0] * r, g1 = acc[ai][0][m][1] * r, u0 = acc[ai][1][m][0] * r, u1 = acc[ai][1][m][1] * r;
;                 f32x4 h0, h1;
;                 h0.x = silu_f(g0.x) * u0.x; h0.y = silu_f(g0.y) * u0.y; h0.z = silu_f(g0.z) * u0.z; h0.w = silu_f(g0.w) * u0.w;
;                 h1.x = silu_f(g1.x) * u1.x; h1.y = silu_f(g1.y) * u1.y; h1.z = silu_f(g1.z) * u1.z; h1.w = silu_f(g1.w) * u1.w;
;                 *(u32x4*)(hb + (wr * 64 + fr + ai * 128 + m * 16) * 64) = pack8(h0, h1);
;             }
	v_rcp_f32_e32 v189, v189
	v_rcp_f32_e32 v190, v190
	v_rcp_f32_e32 v191, v191
	v_rcp_f32_e32 v192, v192
	v_rcp_f32_e32 v193, v193
	v_pk_mul_f32 v[186:187], v[76:77], v[186:187]
	v_pk_mul_f32 v[188:189], v[78:79], v[188:189]
	v_pk_mul_f32 v[190:191], v[72:73], v[190:191]
	v_pk_mul_f32 v[192:193], v[74:75], v[192:193]
	v_pk_mul_f32 v[186:187], v[186:187], v[68:69]
	v_pk_mul_f32 v[188:189], v[188:189], v[70:71]
	v_pk_mul_f32 v[190:191], v[190:191], v[64:65]
	v_pk_mul_f32 v[192:193], v[192:193], v[66:67]
	v_cvt_pk_bf16_f32 v64, v186, v187
	v_cvt_pk_bf16_f32 v65, v188, v189
	v_cvt_pk_bf16_f32 v66, v190, v191
	v_cvt_pk_bf16_f32 v67, v192, v193
	global_store_dwordx4 v[170:171], v[64:67], off offset:2048
	v_pk_mul_f32 v[178:179], v[60:61], v[162:163]
	v_pk_mul_f32 v[180:181], v[62:63], v[162:163]
	v_pk_mul_f32 v[182:183], v[56:57], v[162:163]
	v_pk_mul_f32 v[184:185], v[58:59], v[162:163]
	v_exp_f32_e32 v178, v178
	v_exp_f32_e32 v179, v179
	v_exp_f32_e32 v180, v180
	v_exp_f32_e32 v181, v181
	v_exp_f32_e32 v182, v182
	v_exp_f32_e32 v183, v183
	v_exp_f32_e32 v184, v184
	v_exp_f32_e32 v185, v185
	v_pk_add_f32 v[178:179], v[178:179], v[164:165]
	v_pk_add_f32 v[180:181], v[180:181], v[164:165]
	v_pk_add_f32 v[182:183], v[182:183], v[164:165]
	v_pk_add_f32 v[184:185], v[184:185], v[164:165]
	v_rcp_f32_e32 v178, v178
	v_rcp_f32_e32 v179, v179
	v_rcp_f32_e32 v180, v180
	v_rcp_f32_e32 v181, v181
	v_rcp_f32_e32 v182, v182
	v_rcp_f32_e32 v183, v183
	v_rcp_f32_e32 v184, v184
	v_rcp_f32_e32 v185, v185
	v_pk_mul_f32 v[178:179], v[60:61], v[178:179]
	v_pk_mul_f32 v[180:181], v[62:63], v[180:181]
	v_pk_mul_f32 v[182:183], v[56:57], v[182:183]
	v_pk_mul_f32 v[184:185], v[58:59], v[184:185]
	v_pk_mul_f32 v[178:179], v[178:179], v[52:53]
	v_pk_mul_f32 v[180:181], v[180:181], v[54:55]
	v_pk_mul_f32 v[182:183], v[182:183], v[48:49]
	v_pk_mul_f32 v[184:185], v[184:185], v[50:51]
	v_cvt_pk_bf16_f32 v48, v178, v179
	v_cvt_pk_bf16_f32 v49, v180, v181
	v_cvt_pk_bf16_f32 v50, v182, v183
	v_cvt_pk_bf16_f32 v51, v184, v185
	global_store_dwordx4 v[172:173], v[48:51], off
	v_pk_mul_f32 v[186:187], v[44:45], v[162:163]
	v_pk_mul_f32 v[188:189], v[46:47], v[162:163]
	v_pk_mul_f32 v[190:191], v[40:41], v[162:163]
	v_pk_mul_f32 v[192:193], v[42:43], v[162:163]
	v_exp_f32_e32 v186, v186
	v_exp_f32_e32 v187, v187
	v_exp_f32_e32 v188, v188
	v_exp_f32_e32 v189, v189
	v_exp_f32_e32 v190, v190
	v_exp_f32_e32 v191, v191
	v_exp_f32_e32 v192, v192
	v_exp_f32_e32 v193, v193
	v_pk_add_f32 v[186:187], v[186:187], v[164:165]
	v_pk_add_f32 v[188:189], v[188:189], v[164:165]
	v_pk_add_f32 v[190:191], v[190:191], v[164:165]
	v_pk_add_f32 v[192:193], v[192:193], v[164:165]
	v_rcp_f32_e32 v186, v186
	v_rcp_f32_e32 v187, v187
	v_rcp_f32_e32 v188, v188
	v_rcp_f32_e32 v189, v189
	v_rcp_f32_e32 v190, v190
	v_rcp_f32_e32 v191, v191
	v_rcp_f32_e32 v192, v192
	v_rcp_f32_e32 v193, v193
	v_pk_mul_f32 v[186:187], v[44:45], v[186:187]
	v_pk_mul_f32 v[188:189], v[46:47], v[188:189]
	v_pk_mul_f32 v[190:191], v[40:41], v[190:191]
	v_pk_mul_f32 v[192:193], v[42:43], v[192:193]
	v_pk_mul_f32 v[186:187], v[186:187], v[36:37]
	v_pk_mul_f32 v[188:189], v[188:189], v[38:39]
	v_pk_mul_f32 v[190:191], v[190:191], v[32:33]
	v_pk_mul_f32 v[192:193], v[192:193], v[34:35]
	v_cvt_pk_bf16_f32 v32, v186, v187
	v_cvt_pk_bf16_f32 v33, v188, v189
	v_cvt_pk_bf16_f32 v34, v190, v191
	v_cvt_pk_bf16_f32 v35, v192, v193
	global_store_dwordx4 v[174:175], v[32:35], off
	v_pk_mul_f32 v[178:179], v[28:29], v[162:163]
	v_pk_mul_f32 v[180:181], v[30:31], v[162:163]
	v_pk_mul_f32 v[182:183], v[24:25], v[162:163]
	v_pk_mul_f32 v[184:185], v[26:27], v[162:163]
	v_exp_f32_e32 v178, v178
	v_exp_f32_e32 v179, v179
	v_exp_f32_e32 v180, v180
	v_exp_f32_e32 v181, v181
	v_exp_f32_e32 v182, v182
	v_exp_f32_e32 v183, v183
	v_exp_f32_e32 v184, v184
	v_exp_f32_e32 v185, v185
	v_pk_add_f32 v[178:179], v[178:179], v[164:165]
	v_pk_add_f32 v[180:181], v[180:181], v[164:165]
	v_pk_add_f32 v[182:183], v[182:183], v[164:165]
	v_pk_add_f32 v[184:185], v[184:185], v[164:165]
	v_rcp_f32_e32 v178, v178
	v_rcp_f32_e32 v179, v179
	v_rcp_f32_e32 v180, v180
	v_rcp_f32_e32 v181, v181
	v_rcp_f32_e32 v182, v182
	v_rcp_f32_e32 v183, v183
	v_rcp_f32_e32 v184, v184
	v_rcp_f32_e32 v185, v185
	v_pk_mul_f32 v[178:179], v[28:29], v[178:179]
	v_pk_mul_f32 v[180:181], v[30:31], v[180:181]
	v_pk_mul_f32 v[182:183], v[24:25], v[182:183]
	v_pk_mul_f32 v[184:185], v[26:27], v[184:185]
	v_pk_mul_f32 v[178:179], v[178:179], v[20:21]
	v_pk_mul_f32 v[180:181], v[180:181], v[22:23]
	v_pk_mul_f32 v[182:183], v[182:183], v[16:17]
	v_pk_mul_f32 v[184:185], v[184:185], v[18:19]
	v_cvt_pk_bf16_f32 v16, v178, v179
	v_cvt_pk_bf16_f32 v17, v180, v181
	v_cvt_pk_bf16_f32 v18, v182, v183
	v_cvt_pk_bf16_f32 v19, v184, v185
	global_store_dwordx4 v[176:177], v[16:19], off
	v_pk_mul_f32 v[186:187], v[12:13], v[162:163]
	v_pk_mul_f32 v[188:189], v[14:15], v[162:163]
	v_pk_mul_f32 v[190:191], v[8:9], v[162:163]
	v_pk_mul_f32 v[192:193], v[10:11], v[162:163]
	v_exp_f32_e32 v186, v186
	v_exp_f32_e32 v187, v187
	v_exp_f32_e32 v188, v188
	v_exp_f32_e32 v189, v189
	v_exp_f32_e32 v190, v190
	v_exp_f32_e32 v191, v191
	v_exp_f32_e32 v192, v192
	v_exp_f32_e32 v193, v193
	v_pk_add_f32 v[186:187], v[186:187], v[164:165]
	v_pk_add_f32 v[188:189], v[188:189], v[164:165]
	v_pk_add_f32 v[190:191], v[190:191], v[164:165]
	v_pk_add_f32 v[192:193], v[192:193], v[164:165]
	v_rcp_f32_e32 v186, v186
	v_rcp_f32_e32 v187, v187
	v_rcp_f32_e32 v188, v188
	v_rcp_f32_e32 v189, v189
	v_rcp_f32_e32 v190, v190
	v_rcp_f32_e32 v191, v191
	v_rcp_f32_e32 v192, v192
	v_rcp_f32_e32 v193, v193
	v_pk_mul_f32 v[186:187], v[12:13], v[186:187]
	v_pk_mul_f32 v[188:189], v[14:15], v[188:189]
	v_pk_mul_f32 v[190:191], v[8:9], v[190:191]
	v_pk_mul_f32 v[192:193], v[10:11], v[192:193]
	v_pk_mul_f32 v[186:187], v[186:187], v[4:5]
	v_pk_mul_f32 v[188:189], v[188:189], v[6:7]
	v_pk_mul_f32 v[190:191], v[190:191], v[0:1]
	v_pk_mul_f32 v[192:193], v[192:193], v[2:3]
	v_cvt_pk_bf16_f32 v0, v186, v187
	v_cvt_pk_bf16_f32 v1, v188, v189
	v_cvt_pk_bf16_f32 v2, v190, v191
	v_cvt_pk_bf16_f32 v3, v192, v193
	global_store_dwordx4 v[194:195], v[0:3], off
	s_andn2_b64 vcc, exec, s[0:1]
	s_mov_b64 s[0:1], -1
	s_cbranch_vccnz .LBB0_171
	s_andn2_b64 vcc, exec, s[6:7]
	s_cbranch_vccnz .LBB0_170
	s_barrier
	s_branch .LBB0_170

; __device__ __forceinline__ float silu_f(float g) { return g * __builtin_amdgcn_rcpf(1.f + __builtin_amdgcn_exp2f(-1.4426950408889634f * g)); }
; __device__ __forceinline__ u32x4 pack8(f32x4 a, f32x4 b) { u32x4 o; o.x = cvt_pk(a.x, a.y); o.y = cvt_pk(a.z, a.w); o.z = cvt_pk(b.x, b.y); o.w = cvt_pk(b.z, b.w); return o; }
; __device__ __forceinline__ float rstd_of(const float* SS, int row, float invw) { return 1.0f / sqrtf(SS[row] * invw + EPS); }
;     __device__ __forceinline__ void operator()(const f32x4 (&acc)[2][2][4][2], const pg8::Unit& u, int wr, int wc, int fr, int fq) const {
;         const int row0 = u.pm * 256 + wr * 64 + fr, col0 = u.pn * 128 + wc * 32 + 8 * fq;
;         bf16_t* hb = H + (size_t)u.pm * 256 * FF + (size_t)(col0 >> 6) * (256 * 64) + (col0 & 63);
; #pragma unroll
;         for (int ai = 0; ai < 2; ++ai)
; #pragma unroll
;             for (int m = 0; m < 4; ++m) {
;                 const int row = row0 + ai * 128 + m * 16;
;                 const float r = SCALE ? rstd_of(SS, row, 1.f / 1024.f) : 1.f;
;                 const f32x4 g0 = acc[ai][0][m][0] * r, g1 = acc[ai][0][m][1] * r, u0 = acc[ai][1][m][0] * r, u1 = acc[ai][1][m][1] * r;
;                 f32x4 h0, h1;
;                 h0.x = silu_f(g0.x) * u0.x; h0.y = silu_f(g0.y) * u0.y; h0.z = silu_f(g0.z) * u0.z; h0.w = silu_f(g0.w) * u0.w;
;                 h1.x = silu_f(g1.x) * u1.x; h1.y = silu_f(g1.y) * u1.y; h1.z = silu_f(g1.z) * u1.z; h1.w = silu_f(g1.w) * u1.w;
;                 *(u32x4*)(hb + (wr * 64 + fr + ai * 128 + m * 16) * 64) = pack8(h0, h1);
;             }
.LBB0_827:
	v_lshl_add_u32 v158, s0, 8, v160
	v_ashrrev_i32_e32 v159, 31, v158
	v_lshl_add_u64 v[158:159], v[158:159], 2, s[44:45]
	global_load_dword v200, v[158:159], off
	global_load_dword v201, v[158:159], off offset:64
	global_load_dword v202, v[158:159], off offset:128
	global_load_dword v203, v[158:159], off offset:192
	global_load_dword v204, v[158:159], off offset:512
	global_load_dword v205, v[158:159], off offset:576
	global_load_dword v206, v[158:159], off offset:640
	global_load_dword v207, v[158:159], off offset:704
	s_lshl_b32 s1, s1, 7
	s_or_b32 s1, s1, s67
	s_mul_hi_i32 s4, s0, 0x160000
	s_mul_i32 s0, s0, 0x160000
	s_add_u32 s5, s64, s0
	s_addc_u32 s4, s65, s4
	s_ashr_i32 s0, s1, 6
	s_ashr_i32 s1, s0, 31
	s_lshl_b64 s[0:1], s[0:1], 15
	s_add_u32 s0, s5, s0
	s_addc_u32 s1, s4, s1
	v_lshl_add_u64 v[156:157], s[0:1], 0, v[136:137]
	v_mov_b32_e32 v208, 0xbfb8aa3b
	v_mov_b32_e32 v209, 0xbfb8aa3b
	v_mov_b32_e32 v210, 1.0
	v_mov_b32_e32 v211, 1.0
	s_movk_i32 s0, 0x1000
	v_lshl_add_u64 v[212:213], v[138:139], 1, v[156:157]
	v_add_co_u32_e32 v214, vcc, s0, v212
	v_addc_co_u32_e32 v215, vcc, 0, v213, vcc
	v_lshl_add_u64 v[216:217], v[140:141], 1, v[156:157]
	v_lshl_add_u64 v[218:219], v[142:143], 1, v[156:157]
	v_lshl_add_u64 v[220:221], v[144:145], 1, v[156:157]
	v_lshl_add_u64 v[222:223], v[146:147], 1, v[156:157]
	s_waitcnt vmcnt(0)
	v_fmamk_f32 v200, v200, 0x3a800000, v165
	v_fmamk_f32 v201, v201, 0x3a800000, v165
	v_fmamk_f32 v202, v202, 0x3a800000, v165
	v_fmamk_f32 v203, v203, 0x3a800000, v165
	v_fmamk_f32 v204, v204, 0x3a800000, v165
	v_fmamk_f32 v205, v205, 0x3a800000, v165
	v_fmamk_f32 v206, v206, 0x3a800000, v165
	v_fmamk_f32 v207, v207, 0x3a800000, v165
	v_rsq_f32_e32 v200, v200
	v_rsq_f32_e32 v201, v201
	v_rsq_f32_e32 v202, v202
	v_rsq_f32_e32 v203, v203
	v_rsq_f32_e32 v204, v204
	v_rsq_f32_e32 v205, v205
	v_rsq_f32_e32 v206, v206
	v_rsq_f32_e32 v207, v207
	v_pk_mul_f32 v[124:125], v[124:125], v[200:201] op_sel_hi:[1,0]
	v_pk_mul_f32 v[126:127], v[126:127], v[200:201] op_sel_hi:[1,0]
	v_pk_mul_f32 v[120:121], v[120:121], v[200:201] op_sel_hi:[1,0]
	v_pk_mul_f32 v[122:123], v[122:123], v[200:201] op_sel_hi:[1,0]
	v_pk_mul_f32 v[116:117], v[116:117], v[200:201] op_sel_hi:[1,0]
	v_pk_mul_f32 v[118:119], v[118:119], v[200:201] op_sel_hi:[1,0]
	v_pk_mul_f32 v[112:113], v[112:113], v[200:201] op_sel_hi:[1,0]
	v_pk_mul_f32 v[114:115], v[114:115], v[200:201] op_sel_hi:[1,0]
	v_pk_mul_f32 v[168:169], v[124:125], v[208:209]
	v_pk_mul_f32 v[170:171], v[126:127], v[208:209]
	v_pk_mul_f32 v[172:173], v[120:121], v[208:209]
	v_pk_mul_f32 v[174:175], v[122:123], v[208:209]
	v_exp_f32_e32 v168, v168
	v_exp_f32_e32 v169, v169
	v_exp_f32_e32 v170, v170
	v_exp_f32_e32 v171, v171
	v_exp_f32_e32 v172, v172
	v_exp_f32_e32 v173, v173
	v_exp_f32_e32 v174, v174
	v_exp_f32_e32 v175, v175
	v_pk_add_f32 v[168:169], v[168:169], v[210:211]
	v_pk_add_f32 v[170:171], v[170:171], v[210:211]
	v_pk_add_f32 v[172:173], v[172:173], v[210:211]
	v_pk_add_f32 v[174:175], v[174:175], v[210:211]
	v_rcp_f32_e32 v168, v168
	v_rcp_f32_e32 v169, v169
	v_rcp_f32_e32 v170, v170
	v_rcp_f32_e32 v171, v171
	v_rcp_f32_e32 v172, v172
	v_rcp_f32_e32 v173, v173
	v_rcp_f32_e32 v174, v174
	v_rcp_f32_e32 v175, v175
	v_pk_mul_f32 v[168:169], v[124:125], v[168:169]
	v_pk_mul_f32 v[170:171], v[126:127], v[170:171]
	v_pk_mul_f32 v[172:173], v[120:121], v[172:173]
	v_pk_mul_f32 v[174:175], v[122:123], v[174:175]
	v_pk_mul_f32 v[168:169], v[116:117], v[168:169]
	v_pk_mul_f32 v[170:171], v[118:119], v[170:171]
	v_pk_mul_f32 v[172:173], v[112:113], v[172:173]
	v_pk_mul_f32 v[174:175], v[114:115], v[174:175]
	v_cvt_pk_bf16_f32 v112, v168, v169
	v_cvt_pk_bf16_f32 v113, v170, v171
	v_cvt_pk_bf16_f32 v114, v172, v173
	v_cvt_pk_bf16_f32 v115, v174, v175
	global_store_dwordx4 v[212:213], v[112:115], off
	v_pk_mul_f32 v[108:109], v[108:109], v[200:201] op_sel:[0,1] op_sel_hi:[1,1]
	v_pk_mul_f32 v[110:111], v[110:111], v[200:201] op_sel:[0,1] op_sel_hi:[1,1]
	v_pk_mul_f32 v[104:105], v[104:105], v[200:201] op_sel:[0,1] op_sel_hi:[1,1]
	v_pk_mul_f32 v[106:107], v[106:107], v[200:201] op_sel:[0,1] op_sel_hi:[1,1]
	v_pk_mul_f32 v[100:101], v[100:101], v[200:201] op_sel:[0,1] op_sel_hi:[1,1]
	v_pk_mul_f32 v[102:103], v[102:103], v[200:201] op_sel:[0,1] op_sel_hi:[1,1]
	v_pk_mul_f32 v[96:97], v[96:97], v[200:201] op_sel:[0,1] op_sel_hi:[1,1]
	v_pk_mul_f32 v[98:99], v[98:99], v[200:201] op_sel:[0,1] op_sel_hi:[1,1]
	v_pk_mul_f32 v[176:177], v[108:109], v[208:209]
	v_pk_mul_f32 v[178:179], v[110:111], v[208:209]
	v_pk_mul_f32 v[180:181], v[104:105], v[208:209]
	v_pk_mul_f32 v[182:183], v[106:107], v[208:209]
	v_exp_f32_e32 v176, v176
	v_exp_f32_e32 v177, v177
	v_exp_f32_e32 v178, v178
	v_exp_f32_e32 v179, v179
	v_exp_f32_e32 v180, v180
	v_exp_f32_e32 v181, v181
	v_exp_f32_e32 v182, v182
	v_exp_f32_e32 v183, v183
	v_pk_add_f32 v[176:177], v[176:177], v[210:211]
	v_pk_add_f32 v[178:179], v[178:179], v[210:211]
	v_pk_add_f32 v[180:181], v[180:181], v[210:211]
	v_pk_add_f32 v[182:183], v[182:183], v[210:211]
	v_rcp_f32_e32 v176, v176
	v_rcp_f32_e32 v177, v177
	v_rcp_f32_e32 v178, v178
	v_rcp_f32_e32 v179, v179
	v_rcp_f32_e32 v180, v180
	v_rcp_f32_e32 v181, v181
	v_rcp_f32_e32 v182, v182
	v_rcp_f32_e32 v183, v183
	v_pk_mul_f32 v[176:177], v[108:109], v[176:177]
	v_pk_mul_f32 v[178:179], v[110:111], v[178:179]
	v_pk_mul_f32 v[180:181], v[104:105], v[180:181]
	v_pk_mul_f32 v[182:183], v[106:107], v[182:183]
	v_pk_mul_f32 v[176:177], v[100:101], v[176:177]
	v_pk_mul_f32 v[178:179], v[102:103], v[178:179]
	v_pk_mul_f32 v[180:181], v[96:97], v[180:181]
	v_pk_mul_f32 v[182:183], v[98:99], v[182:183]
; __device__ __forceinline__ float silu_f(float g) { return g * __builtin_amdgcn_rcpf(1.f + __builtin_amdgcn_exp2f(-1.4426950408889634f * g)); }
; __device__ __forceinline__ u32x4 pack8(f32x4 a, f32x4 b) { u32x4 o; o.x = cvt_pk(a.x, a.y); o.y = cvt_pk(a.z, a.w); o.z = cvt_pk(b.x, b.y); o.w = cvt_pk(b.z, b.w); return o; }
; __device__ __forceinline__ float rstd_of(const float* SS, int row, float invw) { return 1.0f / sqrtf(SS[row] * invw + EPS); }
;     __device__ __forceinline__ void operator()(const f32x4 (&acc)[2][2][4][2], const pg8::Unit& u, int wr, int wc, int fr, int fq) const {
;     ...
;         for (int ai = 0; ai < 2; ++ai)
; #pragma unroll
;             for (int m = 0; m < 4; ++m) {
;                 const int row = row0 + ai * 128 + m * 16;
;                 const float r = SCALE ? rstd_of(SS, row, 1.f / 1024.f) : 1.f;
;                 const f32x4 g0 = acc[ai][0][m][0] * r, g1 = acc[ai][0][m][1] * r, u0 = acc[ai][1][m][0] * r, u1 = acc[ai][1][m][1] * r;
;                 f32x4 h0, h1;
;                 h0.x = silu_f(g0.x) * u0.x; h0.y = silu_f(g0.y) * u0.y; h0.z = silu_f(g0.z) * u0.z; h0.w = silu_f(g0.w) * u0.w;
;                 h1.x = silu_f(g1.x) * u1.x; h1.y = silu_f(g1.y) * u1.y; h1.z = silu_f(g1.z) * u1.z; h1.w = silu_f(g1.w) * u1.w;
;                 *(u32x4*)(hb + (wr * 64 + fr + ai * 128 + m * 16) * 64) = pack8(h0, h1);
;             }
	v_cvt_pk_bf16_f32 v96, v176, v177
	v_cvt_pk_bf16_f32 v97, v178, v179
	v_cvt_pk_bf16_f32 v98, v180, v181
	v_cvt_pk_bf16_f32 v99, v182, v183
	global_store_dwordx4 v[212:213], v[96:99], off offset:2048
	v_pk_mul_f32 v[92:93], v[92:93], v[202:203] op_sel_hi:[1,0]
	v_pk_mul_f32 v[94:95], v[94:95], v[202:203] op_sel_hi:[1,0]
	v_pk_mul_f32 v[88:89], v[88:89], v[202:203] op_sel_hi:[1,0]
	v_pk_mul_f32 v[90:91], v[90:91], v[202:203] op_sel_hi:[1,0]
	v_pk_mul_f32 v[84:85], v[84:85], v[202:203] op_sel_hi:[1,0]
	v_pk_mul_f32 v[86:87], v[86:87], v[202:203] op_sel_hi:[1,0]
	v_pk_mul_f32 v[80:81], v[80:81], v[202:203] op_sel_hi:[1,0]
	v_pk_mul_f32 v[82:83], v[82:83], v[202:203] op_sel_hi:[1,0]
	v_pk_mul_f32 v[168:169], v[92:93], v[208:209]
	v_pk_mul_f32 v[170:171], v[94:95], v[208:209]
	v_pk_mul_f32 v[172:173], v[88:89], v[208:209]
	v_pk_mul_f32 v[174:175], v[90:91], v[208:209]
	v_exp_f32_e32 v168, v168
	v_exp_f32_e32 v169, v169
	v_exp_f32_e32 v170, v170
	v_exp_f32_e32 v171, v171
	v_exp_f32_e32 v172, v172
	v_exp_f32_e32 v173, v173
	v_exp_f32_e32 v174, v174
	v_exp_f32_e32 v175, v175
	v_pk_add_f32 v[168:169], v[168:169], v[210:211]
	v_pk_add_f32 v[170:171], v[170:171], v[210:211]
	v_pk_add_f32 v[172:173], v[172:173], v[210:211]
	v_pk_add_f32 v[174:175], v[174:175], v[210:211]
	v_rcp_f32_e32 v168, v168
	v_rcp_f32_e32 v169, v169
	v_rcp_f32_e32 v170, v170
	v_rcp_f32_e32 v171, v171
	v_rcp_f32_e32 v172, v172
	v_rcp_f32_e32 v173, v173
	v_rcp_f32_e32 v174, v174
	v_rcp_f32_e32 v175, v175
	v_pk_mul_f32 v[168:169], v[92:93], v[168:169]
	v_pk_mul_f32 v[170:171], v[94:95], v[170:171]
	v_pk_mul_f32 v[172:173], v[88:89], v[172:173]
	v_pk_mul_f32 v[174:175], v[90:91], v[174:175]
	v_pk_mul_f32 v[168:169], v[84:85], v[168:169]
	v_pk_mul_f32 v[170:171], v[86:87], v[170:171]
	v_pk_mul_f32 v[172:173], v[80:81], v[172:173]
	v_pk_mul_f32 v[174:175], v[82:83], v[174:175]
	v_cvt_pk_bf16_f32 v80, v168, v169
	v_cvt_pk_bf16_f32 v81, v170, v171
	v_cvt_pk_bf16_f32 v82, v172, v173
	v_cvt_pk_bf16_f32 v83, v174, v175
	global_store_dwordx4 v[214:215], v[80:83], off
	v_pk_mul_f32 v[76:77], v[76:77], v[202:203] op_sel:[0,1] op_sel_hi:[1,1]
	v_pk_mul_f32 v[78:79], v[78:79], v[202:203] op_sel:[0,1] op_sel_hi:[1,1]
	v_pk_mul_f32 v[72:73], v[72:73], v[202:203] op_sel:[0,1] op_sel_hi:[1,1]
	v_pk_mul_f32 v[74:75], v[74:75], v[202:203] op_sel:[0,1] op_sel_hi:[1,1]
	v_pk_mul_f32 v[68:69], v[68:69], v[202:203] op_sel:[0,1] op_sel_hi:[1,1]
	v_pk_mul_f32 v[70:71], v[70:71], v[202:203] op_sel:[0,1] op_sel_hi:[1,1]
	v_pk_mul_f32 v[64:65], v[64:65], v[202:203] op_sel:[0,1] op_sel_hi:[1,1]
	v_pk_mul_f32 v[66:67], v[66:67], v[202:203] op_sel:[0,1] op_sel_hi:[1,1]
	v_pk_mul_f32 v[176:177], v[76:77], v[208:209]
	v_pk_mul_f32 v[178:179], v[78:79], v[208:209]
	v_pk_mul_f32 v[180:181], v[72:73], v[208:209]
	v_pk_mul_f32 v[182:183], v[74:75], v[208:209]
	v_exp_f32_e32 v176, v176
	v_exp_f32_e32 v177, v177
	v_exp_f32_e32 v178, v178
	v_exp_f32_e32 v179, v179
	v_exp_f32_e32 v180, v180
	v_exp_f32_e32 v181, v181
	v_exp_f32_e32 v182, v182
	v_exp_f32_e32 v183, v183
	v_pk_add_f32 v[176:177], v[176:177], v[210:211]
	v_pk_add_f32 v[178:179], v[178:179], v[210:211]
	v_pk_add_f32 v[180:181], v[180:181], v[210:211]
	v_pk_add_f32 v[182:183], v[182:183], v[210:211]
	v_rcp_f32_e32 v176, v176
	v_rcp_f32_e32 v177, v177
	v_rcp_f32_e32 v178, v178
	v_rcp_f32_e32 v179, v179
	v_rcp_f32_e32 v180, v180
	v_rcp_f32_e32 v181, v181
	v_rcp_f32_e32 v182, v182
	v_rcp_f32_e32 v183, v183
	v_pk_mul_f32 v[176:177], v[76:77], v[176:177]
	v_pk_mul_f32 v[178:179], v[78:79], v[178:179]
	v_pk_mul_f32 v[180:181], v[72:73], v[180:181]
	v_pk_mul_f32 v[182:183], v[74:75], v[182:183]
	v_pk_mul_f32 v[176:177], v[68:69], v[176:177]
	v_pk_mul_f32 v[178:179], v[70:71], v[178:179]
	v_pk_mul_f32 v[180:181], v[64:65], v[180:181]
	v_pk_mul_f32 v[182:183], v[66:67], v[182:183]
	v_cvt_pk_bf16_f32 v64, v176, v177
	v_cvt_pk_bf16_f32 v65, v178, v179
	v_cvt_pk_bf16_f32 v66, v180, v181
	v_cvt_pk_bf16_f32 v67, v182, v183
	global_store_dwordx4 v[214:215], v[64:67], off offset:2048
	v_pk_mul_f32 v[60:61], v[60:61], v[204:205] op_sel_hi:[1,0]
	v_pk_mul_f32 v[62:63], v[62:63], v[204:205] op_sel_hi:[1,0]
	v_pk_mul_f32 v[56:57], v[56:57], v[204:205] op_sel_hi:[1,0]
	v_pk_mul_f32 v[58:59], v[58:59], v[204:205] op_sel_hi:[1,0]
	v_pk_mul_f32 v[52:53], v[52:53], v[204:205] op_sel_hi:[1,0]
	v_pk_mul_f32 v[54:55], v[54:55], v[204:205] op_sel_hi:[1,0]
	v_pk_mul_f32 v[48:49], v[48:49], v[204:205] op_sel_hi:[1,0]
	v_pk_mul_f32 v[50:51], v[50:51], v[204:205] op_sel_hi:[1,0]
	v_pk_mul_f32 v[168:169], v[60:61], v[208:209]
	v_pk_mul_f32 v[170:171], v[62:63], v[208:209]
	v_pk_mul_f32 v[172:173], v[56:57], v[208:209]
	v_pk_mul_f32 v[174:175], v[58:59], v[208:209]
	v_exp_f32_e32 v168, v168
	v_exp_f32_e32 v169, v169
	v_exp_f32_e32 v170, v170
	v_exp_f32_e32 v171, v171
	v_exp_f32_e32 v172, v172
	v_exp_f32_e32 v173, v173
	v_exp_f32_e32 v174, v174
	v_exp_f32_e32 v175, v175
	v_pk_add_f32 v[168:169], v[168:169], v[210:211]
	v_pk_add_f32 v[170:171], v[170:171], v[210:211]
	v_pk_add_f32 v[172:173], v[172:173], v[210:211]
	v_pk_add_f32 v[174:175], v[174:175], v[210:211]
	v_rcp_f32_e32 v168, v168
	v_rcp_f32_e32 v169, v169
	v_rcp_f32_e32 v170, v170
	v_rcp_f32_e32 v171, v171
	v_rcp_f32_e32 v172, v172
	v_rcp_f32_e32 v173, v173
	v_rcp_f32_e32 v174, v174
	v_rcp_f32_e32 v175, v175
	v_pk_mul_f32 v[168:169], v[60:61], v[168:169]
	v_pk_mul_f32 v[170:171], v[62:63], v[170:171]
	v_pk_mul_f32 v[172:173], v[56:57], v[172:173]
	v_pk_mul_f32 v[174:175], v[58:59], v[174:175]
	v_pk_mul_f32 v[168:169], v[52:53], v[168:169]
	v_pk_mul_f32 v[170:171], v[54:55], v[170:171]
	v_pk_mul_f32 v[172:173], v[48:49], v[172:173]
; __device__ __forceinline__ float silu_f(float g) { return g * __builtin_amdgcn_rcpf(1.f + __builtin_amdgcn_exp2f(-1.4426950408889634f * g)); }
; __device__ __forceinline__ u32x4 pack8(f32x4 a, f32x4 b) { u32x4 o; o.x = cvt_pk(a.x, a.y); o.y = cvt_pk(a.z, a.w); o.z = cvt_pk(b.x, b.y); o.w = cvt_pk(b.z, b.w); return o; }
; __device__ __forceinline__ float rstd_of(const float* SS, int row, float invw) { return 1.0f / sqrtf(SS[row] * invw + EPS); }
;     __device__ __forceinline__ void operator()(const f32x4 (&acc)[2][2][4][2], const pg8::Unit& u, int wr, int wc, int fr, int fq) const {
;     ...
;         for (int ai = 0; ai < 2; ++ai)
; #pragma unroll
;             for (int m = 0; m < 4; ++m) {
;                 const int row = row0 + ai * 128 + m * 16;
;                 const float r = SCALE ? rstd_of(SS, row, 1.f / 1024.f) : 1.f;
;                 const f32x4 g0 = acc[ai][0][m][0] * r, g1 = acc[ai][0][m][1] * r, u0 = acc[ai][1][m][0] * r, u1 = acc[ai][1][m][1] * r;
;                 f32x4 h0, h1;
;                 h0.x = silu_f(g0.x) * u0.x; h0.y = silu_f(g0.y) * u0.y; h0.z = silu_f(g0.z) * u0.z; h0.w = silu_f(g0.w) * u0.w;
;                 h1.x = silu_f(g1.x) * u1.x; h1.y = silu_f(g1.y) * u1.y; h1.z = silu_f(g1.z) * u1.z; h1.w = silu_f(g1.w) * u1.w;
;                 *(u32x4*)(hb + (wr * 64 + fr + ai * 128 + m * 16) * 64) = pack8(h0, h1);
;             }
	v_pk_mul_f32 v[174:175], v[50:51], v[174:175]
	v_cvt_pk_bf16_f32 v48, v168, v169
	v_cvt_pk_bf16_f32 v49, v170, v171
	v_cvt_pk_bf16_f32 v50, v172, v173
	v_cvt_pk_bf16_f32 v51, v174, v175
	global_store_dwordx4 v[216:217], v[48:51], off
	v_pk_mul_f32 v[44:45], v[44:45], v[204:205] op_sel:[0,1] op_sel_hi:[1,1]
	v_pk_mul_f32 v[46:47], v[46:47], v[204:205] op_sel:[0,1] op_sel_hi:[1,1]
	v_pk_mul_f32 v[40:41], v[40:41], v[204:205] op_sel:[0,1] op_sel_hi:[1,1]
	v_pk_mul_f32 v[42:43], v[42:43], v[204:205] op_sel:[0,1] op_sel_hi:[1,1]
	v_pk_mul_f32 v[36:37], v[36:37], v[204:205] op_sel:[0,1] op_sel_hi:[1,1]
	v_pk_mul_f32 v[38:39], v[38:39], v[204:205] op_sel:[0,1] op_sel_hi:[1,1]
	v_pk_mul_f32 v[32:33], v[32:33], v[204:205] op_sel:[0,1] op_sel_hi:[1,1]
	v_pk_mul_f32 v[34:35], v[34:35], v[204:205] op_sel:[0,1] op_sel_hi:[1,1]
	v_pk_mul_f32 v[176:177], v[44:45], v[208:209]
	v_pk_mul_f32 v[178:179], v[46:47], v[208:209]
	v_pk_mul_f32 v[180:181], v[40:41], v[208:209]
	v_pk_mul_f32 v[182:183], v[42:43], v[208:209]
	v_exp_f32_e32 v176, v176
	v_exp_f32_e32 v177, v177
	v_exp_f32_e32 v178, v178
	v_exp_f32_e32 v179, v179
	v_exp_f32_e32 v180, v180
	v_exp_f32_e32 v181, v181
	v_exp_f32_e32 v182, v182
	v_exp_f32_e32 v183, v183
	v_pk_add_f32 v[176:177], v[176:177], v[210:211]
	v_pk_add_f32 v[178:179], v[178:179], v[210:211]
	v_pk_add_f32 v[180:181], v[180:181], v[210:211]
	v_pk_add_f32 v[182:183], v[182:183], v[210:211]
	v_rcp_f32_e32 v176, v176
	v_rcp_f32_e32 v177, v177
	v_rcp_f32_e32 v178, v178
	v_rcp_f32_e32 v179, v179
	v_rcp_f32_e32 v180, v180
	v_rcp_f32_e32 v181, v181
	v_rcp_f32_e32 v182, v182
	v_rcp_f32_e32 v183, v183
	v_pk_mul_f32 v[176:177], v[44:45], v[176:177]
	v_pk_mul_f32 v[178:179], v[46:47], v[178:179]
	v_pk_mul_f32 v[180:181], v[40:41], v[180:181]
	v_pk_mul_f32 v[182:183], v[42:43], v[182:183]
	v_pk_mul_f32 v[176:177], v[36:37], v[176:177]
	v_pk_mul_f32 v[178:179], v[38:39], v[178:179]
	v_pk_mul_f32 v[180:181], v[32:33], v[180:181]
	v_pk_mul_f32 v[182:183], v[34:35], v[182:183]
	v_cvt_pk_bf16_f32 v32, v176, v177
	v_cvt_pk_bf16_f32 v33, v178, v179
	v_cvt_pk_bf16_f32 v34, v180, v181
	v_cvt_pk_bf16_f32 v35, v182, v183
	global_store_dwordx4 v[218:219], v[32:35], off
	v_pk_mul_f32 v[28:29], v[28:29], v[206:207] op_sel_hi:[1,0]
	v_pk_mul_f32 v[30:31], v[30:31], v[206:207] op_sel_hi:[1,0]
	v_pk_mul_f32 v[24:25], v[24:25], v[206:207] op_sel_hi:[1,0]
	v_pk_mul_f32 v[26:27], v[26:27], v[206:207] op_sel_hi:[1,0]
	v_pk_mul_f32 v[20:21], v[20:21], v[206:207] op_sel_hi:[1,0]
	v_pk_mul_f32 v[22:23], v[22:23], v[206:207] op_sel_hi:[1,0]
	v_pk_mul_f32 v[16:17], v[16:17], v[206:207] op_sel_hi:[1,0]
	v_pk_mul_f32 v[18:19], v[18:19], v[206:207] op_sel_hi:[1,0]
	v_pk_mul_f32 v[168:169], v[28:29], v[208:209]
	v_pk_mul_f32 v[170:171], v[30:31], v[208:209]
	v_pk_mul_f32 v[172:173], v[24:25], v[208:209]
	v_pk_mul_f32 v[174:175], v[26:27], v[208:209]
	v_exp_f32_e32 v168, v168
	v_exp_f32_e32 v169, v169
	v_exp_f32_e32 v170, v170
	v_exp_f32_e32 v171, v171
	v_exp_f32_e32 v172, v172
	v_exp_f32_e32 v173, v173
	v_exp_f32_e32 v174, v174
	v_exp_f32_e32 v175, v175
	v_pk_add_f32 v[168:169], v[168:169], v[210:211]
	v_pk_add_f32 v[170:171], v[170:171], v[210:211]
	v_pk_add_f32 v[172:173], v[172:173], v[210:211]
	v_pk_add_f32 v[174:175], v[174:175], v[210:211]
	v_rcp_f32_e32 v168, v168
	v_rcp_f32_e32 v169, v169
	v_rcp_f32_e32 v170, v170
	v_rcp_f32_e32 v171, v171
	v_rcp_f32_e32 v172, v172
	v_rcp_f32_e32 v173, v173
	v_rcp_f32_e32 v174, v174
	v_rcp_f32_e32 v175, v175
	v_pk_mul_f32 v[168:169], v[28:29], v[168:169]
	v_pk_mul_f32 v[170:171], v[30:31], v[170:171]
	v_pk_mul_f32 v[172:173], v[24:25], v[172:173]
	v_pk_mul_f32 v[174:175], v[26:27], v[174:175]
	v_pk_mul_f32 v[168:169], v[20:21], v[168:169]
	v_pk_mul_f32 v[170:171], v[22:23], v[170:171]
	v_pk_mul_f32 v[172:173], v[16:17], v[172:173]
	v_pk_mul_f32 v[174:175], v[18:19], v[174:175]
	v_cvt_pk_bf16_f32 v16, v168, v169
	v_cvt_pk_bf16_f32 v17, v170, v171
	v_cvt_pk_bf16_f32 v18, v172, v173
	v_cvt_pk_bf16_f32 v19, v174, v175
	global_store_dwordx4 v[220:221], v[16:19], off
	v_pk_mul_f32 v[12:13], v[12:13], v[206:207] op_sel:[0,1] op_sel_hi:[1,1]
	v_pk_mul_f32 v[14:15], v[14:15], v[206:207] op_sel:[0,1] op_sel_hi:[1,1]
	v_pk_mul_f32 v[8:9], v[8:9], v[206:207] op_sel:[0,1] op_sel_hi:[1,1]
	v_pk_mul_f32 v[10:11], v[10:11], v[206:207] op_sel:[0,1] op_sel_hi:[1,1]
	v_pk_mul_f32 v[4:5], v[4:5], v[206:207] op_sel:[0,1] op_sel_hi:[1,1]
	v_pk_mul_f32 v[6:7], v[6:7], v[206:207] op_sel:[0,1] op_sel_hi:[1,1]
	v_pk_mul_f32 v[0:1], v[0:1], v[206:207] op_sel:[0,1] op_sel_hi:[1,1]
	v_pk_mul_f32 v[2:3], v[2:3], v[206:207] op_sel:[0,1] op_sel_hi:[1,1]
	v_pk_mul_f32 v[176:177], v[12:13], v[208:209]
	v_pk_mul_f32 v[178:179], v[14:15], v[208:209]
	v_pk_mul_f32 v[180:181], v[8:9], v[208:209]
	v_pk_mul_f32 v[182:183], v[10:11], v[208:209]
	v_exp_f32_e32 v176, v176
	v_exp_f32_e32 v177, v177
	v_exp_f32_e32 v178, v178
	v_exp_f32_e32 v179, v179
	v_exp_f32_e32 v180, v180
	v_exp_f32_e32 v181, v181
	v_exp_f32_e32 v182, v182
	v_exp_f32_e32 v183, v183
	v_pk_add_f32 v[176:177], v[176:177], v[210:211]
	v_pk_add_f32 v[178:179], v[178:179], v[210:211]
	v_pk_add_f32 v[180:181], v[180:181], v[210:211]
	v_pk_add_f32 v[182:183], v[182:183], v[210:211]
	v_rcp_f32_e32 v176, v176
	v_rcp_f32_e32 v177, v177
	v_rcp_f32_e32 v178, v178
	v_rcp_f32_e32 v179, v179
	v_rcp_f32_e32 v180, v180
	v_rcp_f32_e32 v181, v181
	v_rcp_f32_e32 v182, v182
	v_rcp_f32_e32 v183, v183
	v_pk_mul_f32 v[176:177], v[12:13], v[176:177]
	v_pk_mul_f32 v[178:179], v[14:15], v[178:179]
	v_pk_mul_f32 v[180:181], v[8:9], v[180:181]
	v_pk_mul_f32 v[182:183], v[10:11], v[182:183]
	v_pk_mul_f32 v[176:177], v[4:5], v[176:177]
	v_pk_mul_f32 v[178:179], v[6:7], v[178:179]
	v_pk_mul_f32 v[180:181], v[0:1], v[180:181]
	v_pk_mul_f32 v[182:183], v[2:3], v[182:183]
	v_cvt_pk_bf16_f32 v0, v176, v177
	v_cvt_pk_bf16_f32 v1, v178, v179
	v_cvt_pk_bf16_f32 v2, v180, v181
	v_cvt_pk_bf16_f32 v3, v182, v183
	global_store_dwordx4 v[222:223], v[0:3], off
	s_mov_b64 s[0:1], -1
	s_andn2_b64 vcc, exec, s[38:39]
	s_cbranch_vccnz .LBB0_820
	s_andn2_b64 vcc, exec, s[28:29]
	s_cbranch_vccnz .LBB0_819
	s_barrier
	s_branch .LBB0_819
